# seams 2 and 9 XCD-local too: converted weights published with write-through stores + arrival counters polled before P3 / P10
# speedup vs baseline: 1.0065x; 1.0065x over previous
.LBB0_100:
	v_ashrrev_i32_e32 v3, 31, v2
	v_lshlrev_b64 v[74:75], 2, v[2:3]
	v_lshl_add_u64 v[70:71], s[0:1], 0, v[74:75]
	s_mov_b32 s27, 0x12000
	v_add_co_u32_e32 v12, vcc, s27, v70
	s_mov_b32 s27, 0x24000
	s_nop 0
	v_addc_co_u32_e32 v13, vcc, 0, v71, vcc
	v_add_co_u32_e32 v16, vcc, s27, v70
	s_mov_b32 s27, 0x36000
	s_nop 0
	v_addc_co_u32_e32 v17, vcc, 0, v71, vcc
	v_add_co_u32_e32 v20, vcc, s27, v70
	v_lshl_add_u64 v[4:5], s[42:43], 0, v[74:75]
	s_nop 0
	v_addc_co_u32_e32 v21, vcc, 0, v71, vcc
	v_add_co_u32_e32 v24, vcc, s12, v70
	global_load_dwordx4 v[4:7], v[4:5], off
	s_nop 0
	v_addc_co_u32_e32 v25, vcc, 0, v71, vcc
	v_add_co_u32_e32 v28, vcc, s13, v70
	global_load_dwordx4 v[8:11], v[70:71], off
	s_nop 0
	global_load_dwordx4 v[12:15], v[12:13], off
	v_addc_co_u32_e32 v29, vcc, 0, v71, vcc
	v_add_co_u32_e32 v32, vcc, s14, v70
	global_load_dwordx4 v[16:19], v[16:17], off
	s_nop 0
	global_load_dwordx4 v[20:23], v[20:21], off
	v_addc_co_u32_e32 v33, vcc, 0, v71, vcc
	v_add_co_u32_e32 v36, vcc, s15, v70
	global_load_dwordx4 v[24:27], v[24:25], off
	s_nop 0
	global_load_dwordx4 v[28:31], v[28:29], off
	v_addc_co_u32_e32 v37, vcc, 0, v71, vcc
	v_add_co_u32_e32 v40, vcc, s16, v70
	global_load_dwordx4 v[32:35], v[32:33], off
	s_nop 0
	global_load_dwordx4 v[36:39], v[36:37], off
	v_addc_co_u32_e32 v41, vcc, 0, v71, vcc
	v_add_co_u32_e32 v44, vcc, s17, v70
	v_add_u32_e32 v1, s10, v1
	s_nop 0
	v_addc_co_u32_e32 v45, vcc, 0, v71, vcc
	v_add_co_u32_e32 v48, vcc, s18, v70
	global_load_dwordx4 v[40:43], v[40:41], off
	s_nop 0
	global_load_dwordx4 v[44:47], v[44:45], off
	v_addc_co_u32_e32 v49, vcc, 0, v71, vcc
	v_add_co_u32_e32 v52, vcc, s19, v70
	v_add_u32_e32 v2, s11, v2
	s_nop 0
	v_addc_co_u32_e32 v53, vcc, 0, v71, vcc
	v_add_co_u32_e32 v56, vcc, s22, v70
	global_load_dwordx4 v[48:51], v[48:49], off
	s_nop 0
	global_load_dwordx4 v[52:55], v[52:53], off
	v_addc_co_u32_e32 v57, vcc, 0, v71, vcc
	v_add_co_u32_e32 v60, vcc, s23, v70
	s_waitcnt vmcnt(11)
	v_pk_add_f32 v[6:7], v[6:7], v[10:11]
	v_addc_co_u32_e32 v61, vcc, 0, v71, vcc
	v_add_co_u32_e32 v66, vcc, s24, v70
	global_load_dwordx4 v[56:59], v[56:57], off
	s_nop 0
	global_load_dwordx4 v[60:63], v[60:61], off
	v_addc_co_u32_e32 v67, vcc, 0, v71, vcc
	v_add_co_u32_e32 v70, vcc, s25, v70
	global_load_dwordx4 v[66:69], v[66:67], off
	s_nop 0
	v_addc_co_u32_e32 v71, vcc, 0, v71, vcc
	global_load_dwordx4 v[70:73], v[70:71], off
	v_pk_add_f32 v[4:5], v[4:5], v[8:9]
	s_waitcnt vmcnt(14)
	v_pk_add_f32 v[6:7], v[6:7], v[14:15]
	v_pk_add_f32 v[4:5], v[4:5], v[12:13]
	s_waitcnt vmcnt(13)
	v_pk_add_f32 v[6:7], v[6:7], v[18:19]
	v_pk_add_f32 v[4:5], v[4:5], v[16:17]
	s_waitcnt vmcnt(12)
	v_pk_add_f32 v[6:7], v[6:7], v[22:23]
	v_pk_add_f32 v[4:5], v[4:5], v[20:21]
	s_waitcnt vmcnt(11)
	v_pk_add_f32 v[6:7], v[6:7], v[26:27]
	v_pk_add_f32 v[4:5], v[4:5], v[24:25]
	s_waitcnt vmcnt(10)
	v_pk_add_f32 v[6:7], v[6:7], v[30:31]
	v_pk_add_f32 v[4:5], v[4:5], v[28:29]
	s_waitcnt vmcnt(9)
	v_pk_add_f32 v[6:7], v[6:7], v[34:35]
	v_pk_add_f32 v[4:5], v[4:5], v[32:33]
	s_waitcnt vmcnt(8)
	v_pk_add_f32 v[6:7], v[6:7], v[38:39]
	v_pk_add_f32 v[4:5], v[4:5], v[36:37]
	s_waitcnt vmcnt(7)
	v_pk_add_f32 v[6:7], v[6:7], v[42:43]
	v_pk_add_f32 v[4:5], v[4:5], v[40:41]
	s_waitcnt vmcnt(6)
	v_pk_add_f32 v[6:7], v[6:7], v[46:47]
	v_pk_add_f32 v[4:5], v[4:5], v[44:45]
	v_cmp_lt_i32_e32 vcc, s26, v1
	v_lshl_add_u64 v[8:9], s[6:7], 0, v[74:75]
	s_waitcnt vmcnt(5)
	v_pk_add_f32 v[6:7], v[6:7], v[50:51]
	v_pk_add_f32 v[4:5], v[4:5], v[48:49]
	s_waitcnt vmcnt(4)
	v_pk_add_f32 v[6:7], v[6:7], v[54:55]
	v_pk_add_f32 v[4:5], v[4:5], v[52:53]
	s_or_b64 s[8:9], vcc, s[8:9]
	s_waitcnt vmcnt(3)
	v_pk_add_f32 v[6:7], v[6:7], v[58:59]
	v_pk_add_f32 v[4:5], v[4:5], v[56:57]
	s_waitcnt vmcnt(2)
	v_pk_add_f32 v[6:7], v[6:7], v[62:63]
	v_pk_add_f32 v[4:5], v[4:5], v[60:61]
	s_waitcnt vmcnt(1)
	v_pk_add_f32 v[6:7], v[6:7], v[68:69]
	v_pk_add_f32 v[4:5], v[4:5], v[66:67]
	s_waitcnt vmcnt(0)
	v_pk_add_f32 v[6:7], v[6:7], v[72:73]
	v_pk_add_f32 v[4:5], v[4:5], v[70:71]
	global_store_dwordx4 v[8:9], v[4:7], off sc1
	s_andn2_b64 exec, exec, s[8:9]
	s_cbranch_execnz .LBB0_100
	s_or_b64 exec, exec, s[8:9]

.LBB0_164:
	v_mul_u32_u24_e32 v2, s8, v1
	v_lshlrev_b32_e32 v2, 2, v2
	v_lshl_add_u64 v[22:23], s[6:7], 0, v[2:3]
	v_lshl_add_u64 v[22:23], v[22:23], 0, v[4:5]
	s_lshl_b64 s[6:7], s[8:9], 3
	v_lshl_add_u64 v[24:25], v[22:23], 0, s[6:7]
	v_lshl_add_u64 v[26:27], v[24:25], 0, s[6:7]
	v_lshl_add_u64 v[28:29], v[26:27], 0, s[6:7]
	v_lshl_add_u64 v[30:31], v[28:29], 0, s[6:7]
	v_lshl_add_u64 v[32:33], v[30:31], 0, s[6:7]
	v_lshl_add_u64 v[34:35], v[32:33], 0, s[6:7]
	v_lshl_add_u64 v[36:37], v[34:35], 0, s[6:7]
	global_load_dword v2, v[22:23], off nt
	global_load_dword v21, v[24:25], off nt
	s_nop 0
	global_load_dword v24, v[26:27], off nt
	global_load_dword v25, v[28:29], off nt
	s_nop 0
	global_load_dword v26, v[30:31], off nt
	global_load_dword v27, v[32:33], off nt
	global_load_dword v28, v[34:35], off nt
	global_load_dword v29, v[36:37], off nt
	v_lshl_add_u64 v[22:23], v[36:37], 0, s[6:7]
	global_load_dword v30, v[22:23], off nt
	v_lshl_add_u64 v[22:23], v[22:23], 0, s[6:7]
	global_load_dword v31, v[22:23], off nt
	v_lshl_add_u64 v[22:23], v[22:23], 0, s[6:7]
	global_load_dword v32, v[22:23], off nt
	v_lshl_add_u64 v[22:23], v[22:23], 0, s[6:7]
	global_load_dword v33, v[22:23], off nt
	v_lshl_add_u64 v[22:23], v[22:23], 0, s[6:7]
	global_load_dword v34, v[22:23], off nt
	v_lshl_add_u64 v[22:23], v[22:23], 0, s[6:7]
	global_load_dword v35, v[22:23], off nt
	v_lshl_add_u64 v[22:23], v[22:23], 0, s[6:7]
	global_load_dword v36, v[22:23], off nt
	v_lshl_add_u64 v[22:23], v[22:23], 0, s[6:7]
	global_load_dword v37, v[22:23], off nt
	v_lshl_add_u64 v[22:23], v[22:23], 0, s[6:7]
	global_load_dword v38, v[22:23], off nt
	v_lshl_add_u64 v[22:23], v[22:23], 0, s[6:7]
	global_load_dword v39, v[22:23], off nt
	v_lshl_add_u64 v[22:23], v[22:23], 0, s[6:7]
	global_load_dword v40, v[22:23], off nt
	v_lshl_add_u64 v[22:23], v[22:23], 0, s[6:7]
	global_load_dword v41, v[22:23], off nt
	v_lshl_add_u64 v[22:23], v[22:23], 0, s[6:7]
	global_load_dword v42, v[22:23], off nt
	v_lshl_add_u64 v[22:23], v[22:23], 0, s[6:7]
	global_load_dword v43, v[22:23], off nt
	v_lshl_add_u64 v[22:23], v[22:23], 0, s[6:7]
	global_load_dword v44, v[22:23], off nt
	v_lshl_add_u64 v[22:23], v[22:23], 0, s[6:7]
	global_load_dword v45, v[22:23], off nt
	v_lshl_add_u64 v[22:23], v[22:23], 0, s[6:7]
	global_load_dword v46, v[22:23], off nt
	v_lshl_add_u64 v[22:23], v[22:23], 0, s[6:7]
	global_load_dword v47, v[22:23], off nt
	v_lshl_add_u64 v[22:23], v[22:23], 0, s[6:7]
	global_load_dword v48, v[22:23], off nt
	v_lshl_add_u64 v[22:23], v[22:23], 0, s[6:7]
	global_load_dword v49, v[22:23], off nt
	v_lshl_add_u64 v[22:23], v[22:23], 0, s[6:7]
	global_load_dword v50, v[22:23], off nt
	v_lshl_add_u64 v[22:23], v[22:23], 0, s[6:7]
	global_load_dword v51, v[22:23], off nt
	v_lshl_add_u64 v[22:23], v[22:23], 0, s[6:7]
	global_load_dword v52, v[22:23], off nt
	v_lshl_add_u64 v[22:23], v[22:23], 0, s[6:7]
	global_load_dword v22, v[22:23], off nt
	s_add_i32 s13, s13, s12
	s_add_i32 s14, s14, s15
	s_add_i32 s16, s16, s17
	s_cmp_lt_i32 s13, 0x6200
	s_waitcnt vmcnt(30)
	ds_write2_b32 v13, v2, v21 offset1:66
	s_waitcnt vmcnt(28)
	ds_write2_b32 v13, v24, v25 offset0:132 offset1:198
	s_waitcnt vmcnt(26)
	ds_write2_b32 v14, v26, v27 offset0:8 offset1:74
	s_waitcnt vmcnt(24)
	ds_write2_b32 v14, v28, v29 offset0:140 offset1:206
	s_waitcnt vmcnt(22)
	ds_write2_b32 v15, v30, v31 offset0:16 offset1:82
	s_waitcnt vmcnt(20)
	ds_write2_b32 v15, v32, v33 offset0:148 offset1:214
	s_waitcnt vmcnt(18)
	ds_write2_b32 v16, v34, v35 offset0:24 offset1:90
	s_waitcnt vmcnt(16)
	ds_write2_b32 v16, v36, v37 offset0:156 offset1:222
	s_waitcnt vmcnt(14)
	ds_write2_b32 v17, v38, v39 offset0:32 offset1:98
	s_waitcnt vmcnt(12)
	ds_write2_b32 v17, v40, v41 offset0:164 offset1:230
	s_waitcnt vmcnt(10)
	ds_write2_b32 v18, v42, v43 offset0:40 offset1:106
	s_waitcnt vmcnt(8)
	ds_write2_b32 v18, v44, v45 offset0:172 offset1:238
	s_waitcnt vmcnt(6)
	ds_write2_b32 v19, v46, v47 offset0:48 offset1:114
	s_waitcnt vmcnt(4)
	ds_write2_b32 v19, v48, v49 offset0:180 offset1:246
	s_waitcnt vmcnt(2)
	ds_write2_b32 v20, v50, v51 offset0:56 offset1:122
	s_waitcnt vmcnt(0)
	ds_write2_b32 v20, v52, v22 offset0:188 offset1:254
	s_waitcnt lgkmcnt(0)
	ds_read2_b32 v[22:23], v9 offset1:33
	s_waitcnt lgkmcnt(0)
	v_cvt_pk_bf16_f32 v22, v22, v23
	ds_read2_b32 v[24:25], v9 offset0:66 offset1:99
	v_mul_u32_u24_e32 v2, s0, v8
	s_waitcnt lgkmcnt(0)
	v_cvt_pk_bf16_f32 v23, v24, v25
	ds_read2_b32 v[24:25], v9 offset0:132 offset1:165
	v_lshl_add_u64 v[28:29], s[4:5], 0, v[6:7]
	v_lshlrev_b32_e32 v2, 1, v2
	s_waitcnt lgkmcnt(0)
	v_cvt_pk_bf16_f32 v24, v24, v25
	ds_read2_b32 v[26:27], v9 offset0:198 offset1:231
	s_waitcnt lgkmcnt(0)
	v_cvt_pk_bf16_f32 v25, v26, v27
	v_lshl_add_u64 v[30:31], v[28:29], 0, v[2:3]
	ds_read2_b32 v[26:27], v9 offset0:8 offset1:41
	global_store_dwordx4 v[30:31], v[22:25], off sc1
	v_mul_u32_u24_e32 v2, s0, v10
	v_lshlrev_b32_e32 v2, 1, v2
	s_waitcnt lgkmcnt(0)
	v_cvt_pk_bf16_f32 v22, v26, v27
	ds_read2_b32 v[24:25], v9 offset0:74 offset1:107
	s_waitcnt lgkmcnt(0)
	v_cvt_pk_bf16_f32 v23, v24, v25
	ds_read2_b32 v[24:25], v9 offset0:140 offset1:173
	s_waitcnt lgkmcnt(0)
	v_cvt_pk_bf16_f32 v24, v24, v25
	ds_read2_b32 v[26:27], v9 offset0:206 offset1:239
	s_waitcnt lgkmcnt(0)
	v_cvt_pk_bf16_f32 v25, v26, v27
	v_lshl_add_u64 v[30:31], v[28:29], 0, v[2:3]
	ds_read2_b32 v[26:27], v9 offset0:16 offset1:49
	global_store_dwordx4 v[30:31], v[22:25], off sc1
	v_mul_u32_u24_e32 v2, s0, v11
	v_lshlrev_b32_e32 v2, 1, v2
	s_waitcnt lgkmcnt(0)
	v_cvt_pk_bf16_f32 v22, v26, v27
	ds_read2_b32 v[24:25], v9 offset0:82 offset1:115
	s_waitcnt lgkmcnt(0)
	v_cvt_pk_bf16_f32 v23, v24, v25
	ds_read2_b32 v[24:25], v9 offset0:148 offset1:181
	s_waitcnt lgkmcnt(0)
	v_cvt_pk_bf16_f32 v24, v24, v25
	ds_read2_b32 v[26:27], v9 offset0:214 offset1:247
	s_waitcnt lgkmcnt(0)
	v_cvt_pk_bf16_f32 v25, v26, v27
	v_lshl_add_u64 v[30:31], v[28:29], 0, v[2:3]
	v_mul_u32_u24_e32 v2, s0, v12
	ds_read2_b32 v[26:27], v9 offset0:24 offset1:57
	global_store_dwordx4 v[30:31], v[22:25], off sc1
	v_lshlrev_b32_e32 v2, 1, v2
	v_lshl_add_u64 v[28:29], v[28:29], 0, v[2:3]
	s_waitcnt lgkmcnt(0)
	v_cvt_pk_bf16_f32 v22, v26, v27
	ds_read2_b32 v[24:25], v9 offset0:90 offset1:123
	s_waitcnt lgkmcnt(0)
	v_cvt_pk_bf16_f32 v23, v24, v25
	ds_read2_b32 v[24:25], v9 offset0:156 offset1:189
	s_waitcnt lgkmcnt(0)
	v_cvt_pk_bf16_f32 v24, v24, v25
	ds_read2_b32 v[26:27], v9 offset0:222 offset1:255
	s_waitcnt lgkmcnt(0)
	v_cvt_pk_bf16_f32 v25, v26, v27
	global_store_dwordx4 v[28:29], v[22:25], off sc1
	s_waitcnt lgkmcnt(0)
	s_cbranch_scc0 .LBB0_177

.LBB0_177:
	s_waitcnt vmcnt(0)
	s_barrier
	v_cmp_eq_u32_e32 vcc, 0, v146
	s_and_saveexec_b64 s[4:5], vcc
	s_cbranch_execz .Lp2x_pub
	v_mov_b32_e32 v1, 0x6700
	v_mov_b32_e32 v2, 1
	global_atomic_add v1, v2, s[94:95]
.Lp2x_pub:
	s_or_b64 exec, exec, s[4:5]
	s_mov_b64 s[0:1], 0

.LBB0_250:
	v_cmp_eq_u32_e32 vcc, 0, v146
	s_and_saveexec_b64 s[98:99], vcc
	s_cbranch_execz .Lw1_done
	v_mov_b32_e32 v1, 0x6700
	s_mov_b32 s100, 0
.Lw1_poll:
	global_load_dword v2, v1, s[94:95] sc1
	s_waitcnt vmcnt(0)
	v_cmp_gt_u32_e32 vcc, 16, v2
	s_cbranch_vccz .Lw1_done
	s_sleep 2
	s_add_i32 s100, s100, 1
	s_cmp_lt_u32 s100, 0x20000
	s_cbranch_scc1 .Lw1_poll
.Lw1_done:
	s_or_b64 exec, exec, s[98:99]
	s_barrier
	s_cmp_lt_i32 s90, 4
	s_cselect_b64 s[2:3], -1, 0
	s_add_u32 s80, s94, 0x12400000
	s_addc_u32 s81, s95, 0
	s_and_b64 s[2:3], s[2:3], s[0:1]
	s_andn2_b64 vcc, exec, s[2:3]
	s_cbranch_vccnz .LBB0_279
	s_cmpk_gt_i32 s72, 0xff
	v_readfirstlane_b32 s4, v146
	s_cbranch_scc1 .LBB0_279
	s_ashr_i32 s22, s72, 31
	s_lshr_b32 s0, s22, 29
	s_add_i32 s5, s72, s0
	s_and_b32 s0, s5, -8
	s_sub_i32 s7, s72, s0
	s_cmp_gt_i32 s7, -1
	s_cbranch_scc0 .LBB0_254
	s_lshl_b32 s6, s7, 5
	s_cbranch_execz .LBB0_255
	s_branch .LBB0_256

.Lp9x_decode:
	s_add_i32 s0, s6, 0xf800
	s_and_b32 s0, s0, 0xffc0
	s_and_b32 s1, s12, 0x7e0
	s_lshl_b32 s2, s0, 13
	v_readlane_b32 s62, v241, 51
	v_readlane_b32 s63, v241, 52
	s_add_u32 s2, s62, s2
	s_addc_u32 s3, s63, 0
	s_lshl_b32 s4, s1, 2
	s_add_u32 s4, s2, s4
	s_addc_u32 s5, s3, 0
	s_mulk_i32 s1, 0x2c00
	s_add_u32 s1, s22, s1
	s_addc_u32 s3, s23, 0
	s_lshl_b32 s0, s0, 1
	s_add_u32 s2, s1, s0
	s_addc_u32 s3, s3, 0
	s_mov_b64 s[0:1], 0x1600
	v_lshl_add_u64 v[22:23], s[4:5], 0, v[4:5]
	v_lshl_add_u64 v[22:23], v[22:23], 0, v[6:7]
	v_add_co_u32_e32 v24, vcc, 0x4000, v22
	s_add_i32 s6, s6, s7
	s_nop 0
	v_addc_co_u32_e32 v25, vcc, 0, v23, vcc
	v_add_co_u32_e32 v26, vcc, 0x8000, v22
	s_add_i32 s12, s12, s13
	s_nop 0
	v_addc_co_u32_e32 v27, vcc, 0, v23, vcc
	v_add_co_u32_e32 v28, vcc, 0xc000, v22
	s_cmpk_lt_i32 s6, 0x1e00
	s_nop 0
	v_addc_co_u32_e32 v29, vcc, 0, v23, vcc
	v_add_co_u32_e32 v30, vcc, 0x10000, v22
	s_nop 1
	v_addc_co_u32_e32 v31, vcc, 0, v23, vcc
	v_add_co_u32_e32 v32, vcc, 0x14000, v22
	s_nop 1
	v_addc_co_u32_e32 v33, vcc, 0, v23, vcc
	v_add_co_u32_e32 v34, vcc, 0x18000, v22
	s_nop 1
	v_addc_co_u32_e32 v35, vcc, 0, v23, vcc
	v_add_co_u32_e32 v36, vcc, 0x1c000, v22
	s_nop 1
	v_addc_co_u32_e32 v37, vcc, 0, v23, vcc
	global_load_dword v2, v[22:23], off nt
	global_load_dword v40, v[24:25], off nt
	global_load_dword v41, v[26:27], off nt
	global_load_dword v42, v[28:29], off nt
	global_load_dword v43, v[30:31], off nt
	global_load_dword v44, v[32:33], off nt
	global_load_dword v45, v[34:35], off nt
	global_load_dword v46, v[36:37], off nt
	v_add_co_u32_e32 v24, vcc, 0x20000, v22
	s_nop 1
	v_addc_co_u32_e32 v25, vcc, 0, v23, vcc
	v_add_co_u32_e32 v26, vcc, 0x24000, v22
	s_nop 1
	v_addc_co_u32_e32 v27, vcc, 0, v23, vcc
	v_add_co_u32_e32 v28, vcc, 0x28000, v22
	s_nop 1
	v_addc_co_u32_e32 v29, vcc, 0, v23, vcc
	v_add_co_u32_e32 v30, vcc, 0x2c000, v22
	s_nop 1
	v_addc_co_u32_e32 v31, vcc, 0, v23, vcc
	v_add_co_u32_e32 v32, vcc, 0x30000, v22
	s_nop 1
	v_addc_co_u32_e32 v33, vcc, 0, v23, vcc
	v_add_co_u32_e32 v34, vcc, 0x34000, v22
	s_nop 1
	v_addc_co_u32_e32 v35, vcc, 0, v23, vcc
	v_add_co_u32_e32 v36, vcc, 0x38000, v22
	s_nop 1
	v_addc_co_u32_e32 v37, vcc, 0, v23, vcc
	v_add_co_u32_e32 v38, vcc, 0x3c000, v22
	s_nop 1
	v_addc_co_u32_e32 v39, vcc, 0, v23, vcc
	global_load_dword v47, v[24:25], off nt
	global_load_dword v48, v[26:27], off nt
	global_load_dword v49, v[28:29], off nt
	global_load_dword v50, v[30:31], off nt
	global_load_dword v51, v[32:33], off nt
	global_load_dword v52, v[34:35], off nt
	global_load_dword v53, v[36:37], off nt
	global_load_dword v54, v[38:39], off nt
	v_add_co_u32_e32 v24, vcc, 0x40000, v22
	s_nop 1
	v_addc_co_u32_e32 v25, vcc, 0, v23, vcc
	v_add_co_u32_e32 v26, vcc, 0x44000, v22
	s_nop 1
	v_addc_co_u32_e32 v27, vcc, 0, v23, vcc
	v_add_co_u32_e32 v28, vcc, 0x48000, v22
	s_nop 1
	v_addc_co_u32_e32 v29, vcc, 0, v23, vcc
	v_add_co_u32_e32 v30, vcc, 0x4c000, v22
	s_nop 1
	v_addc_co_u32_e32 v31, vcc, 0, v23, vcc
	v_add_co_u32_e32 v32, vcc, 0x50000, v22
	s_nop 1
	v_addc_co_u32_e32 v33, vcc, 0, v23, vcc
	v_add_co_u32_e32 v34, vcc, 0x54000, v22
	s_nop 1
	v_addc_co_u32_e32 v35, vcc, 0, v23, vcc
	v_add_co_u32_e32 v36, vcc, 0x58000, v22
	s_nop 1
	v_addc_co_u32_e32 v37, vcc, 0, v23, vcc
	v_add_co_u32_e32 v38, vcc, 0x5c000, v22
	s_nop 1
	v_addc_co_u32_e32 v39, vcc, 0, v23, vcc
	global_load_dword v55, v[24:25], off nt
	global_load_dword v56, v[26:27], off nt
	global_load_dword v57, v[28:29], off nt
	global_load_dword v58, v[30:31], off nt
	global_load_dword v59, v[32:33], off nt
	global_load_dword v60, v[34:35], off nt
	global_load_dword v61, v[36:37], off nt
	s_nop 0
	global_load_dword v38, v[38:39], off nt
	v_add_co_u32_e32 v24, vcc, 0x60000, v22
	s_nop 1
	v_addc_co_u32_e32 v25, vcc, 0, v23, vcc
	v_add_co_u32_e32 v26, vcc, 0x64000, v22
	s_nop 1
	v_addc_co_u32_e32 v27, vcc, 0, v23, vcc
	v_add_co_u32_e32 v28, vcc, 0x68000, v22
	s_nop 1
	v_addc_co_u32_e32 v29, vcc, 0, v23, vcc
	v_add_co_u32_e32 v30, vcc, 0x6c000, v22
	s_nop 1
	v_addc_co_u32_e32 v31, vcc, 0, v23, vcc
	v_add_co_u32_e32 v32, vcc, 0x70000, v22
	s_nop 1
	v_addc_co_u32_e32 v33, vcc, 0, v23, vcc
	v_add_co_u32_e32 v34, vcc, 0x74000, v22
	s_nop 1
	v_addc_co_u32_e32 v35, vcc, 0, v23, vcc
	v_add_co_u32_e32 v36, vcc, 0x78000, v22
	s_nop 1
	v_addc_co_u32_e32 v37, vcc, 0, v23, vcc
	v_add_co_u32_e32 v22, vcc, 0x7c000, v22
	s_nop 1
	v_addc_co_u32_e32 v23, vcc, 0, v23, vcc
	global_load_dword v24, v[24:25], off nt
	s_nop 0
	global_load_dword v25, v[26:27], off nt
	s_nop 0
	global_load_dword v26, v[28:29], off nt
	global_load_dword v27, v[30:31], off nt
	s_nop 0
	global_load_dword v28, v[32:33], off nt
	global_load_dword v29, v[34:35], off nt
	global_load_dword v30, v[36:37], off nt
	s_nop 0
	global_load_dword v22, v[22:23], off nt
	s_waitcnt vmcnt(0)
	ds_write2_b32 v14, v2, v40 offset1:66
	ds_write2_b32 v14, v41, v42 offset0:132 offset1:198
	ds_write2_b32 v15, v43, v44 offset0:8 offset1:74
	ds_write2_b32 v15, v45, v46 offset0:140 offset1:206
	ds_write2_b32 v16, v47, v48 offset0:16 offset1:82
	ds_write2_b32 v16, v49, v50 offset0:148 offset1:214
	ds_write2_b32 v17, v51, v52 offset0:24 offset1:90
	ds_write2_b32 v17, v53, v54 offset0:156 offset1:222
	ds_write2_b32 v18, v55, v56 offset0:32 offset1:98
	ds_write2_b32 v18, v57, v58 offset0:164 offset1:230
	ds_write2_b32 v19, v59, v60 offset0:40 offset1:106
	ds_write2_b32 v19, v61, v38 offset0:172 offset1:238
	ds_write2_b32 v20, v24, v25 offset0:48 offset1:114
	ds_write2_b32 v20, v26, v27 offset0:180 offset1:246
	ds_write2_b32 v21, v28, v29 offset0:56 offset1:122
	ds_write2_b32 v21, v30, v22 offset0:188 offset1:254
	s_waitcnt lgkmcnt(0)
	ds_read2_b32 v[22:23], v10 offset1:33
	s_waitcnt lgkmcnt(0)
	v_cvt_pk_bf16_f32 v22, v22, v23
	ds_read2_b32 v[24:25], v10 offset0:66 offset1:99
	v_mul_u32_u24_e32 v2, s0, v1
	s_waitcnt lgkmcnt(0)
	v_cvt_pk_bf16_f32 v23, v24, v25
	ds_read2_b32 v[24:25], v10 offset0:132 offset1:165
	v_lshl_add_u64 v[28:29], s[2:3], 0, v[8:9]
	v_lshlrev_b32_e32 v2, 1, v2
	s_waitcnt lgkmcnt(0)
	v_cvt_pk_bf16_f32 v24, v24, v25
	ds_read2_b32 v[26:27], v10 offset0:198 offset1:231
	s_waitcnt lgkmcnt(0)
	v_cvt_pk_bf16_f32 v25, v26, v27
	v_lshl_add_u64 v[30:31], v[28:29], 0, v[2:3]
	ds_read2_b32 v[26:27], v10 offset0:8 offset1:41
	global_store_dwordx4 v[30:31], v[22:25], off sc1
	v_mul_u32_u24_e32 v2, s0, v11
	v_lshlrev_b32_e32 v2, 1, v2
	s_waitcnt lgkmcnt(0)
	v_cvt_pk_bf16_f32 v22, v26, v27
	ds_read2_b32 v[24:25], v10 offset0:74 offset1:107
	s_waitcnt lgkmcnt(0)
	v_cvt_pk_bf16_f32 v23, v24, v25
	ds_read2_b32 v[24:25], v10 offset0:140 offset1:173
	s_waitcnt lgkmcnt(0)
	v_cvt_pk_bf16_f32 v24, v24, v25
	ds_read2_b32 v[26:27], v10 offset0:206 offset1:239
	s_waitcnt lgkmcnt(0)
	v_cvt_pk_bf16_f32 v25, v26, v27
	v_lshl_add_u64 v[30:31], v[28:29], 0, v[2:3]
	ds_read2_b32 v[26:27], v10 offset0:16 offset1:49
	global_store_dwordx4 v[30:31], v[22:25], off sc1
	v_mul_u32_u24_e32 v2, s0, v12
	v_lshlrev_b32_e32 v2, 1, v2
	s_waitcnt lgkmcnt(0)
	v_cvt_pk_bf16_f32 v22, v26, v27
	ds_read2_b32 v[24:25], v10 offset0:82 offset1:115
	s_waitcnt lgkmcnt(0)
	v_cvt_pk_bf16_f32 v23, v24, v25
	ds_read2_b32 v[24:25], v10 offset0:148 offset1:181
	s_waitcnt lgkmcnt(0)
	v_cvt_pk_bf16_f32 v24, v24, v25
	ds_read2_b32 v[26:27], v10 offset0:214 offset1:247
	s_waitcnt lgkmcnt(0)
	v_cvt_pk_bf16_f32 v25, v26, v27
	v_lshl_add_u64 v[30:31], v[28:29], 0, v[2:3]
	ds_read2_b32 v[26:27], v10 offset0:24 offset1:57
	global_store_dwordx4 v[30:31], v[22:25], off sc1
	v_mul_u32_u24_e32 v2, s0, v13
	v_lshlrev_b32_e32 v2, 1, v2
	s_waitcnt lgkmcnt(0)
	v_cvt_pk_bf16_f32 v22, v26, v27
	ds_read2_b32 v[24:25], v10 offset0:90 offset1:123
	s_waitcnt lgkmcnt(0)
	v_cvt_pk_bf16_f32 v23, v24, v25
	ds_read2_b32 v[24:25], v10 offset0:156 offset1:189
	s_waitcnt lgkmcnt(0)
	v_cvt_pk_bf16_f32 v24, v24, v25
	ds_read2_b32 v[26:27], v10 offset0:222 offset1:255
	s_waitcnt lgkmcnt(0)
	v_cvt_pk_bf16_f32 v25, v26, v27
	v_lshl_add_u64 v[26:27], v[28:29], 0, v[2:3]
	global_store_dwordx4 v[26:27], v[22:25], off sc1
	s_waitcnt lgkmcnt(0)
	s_cbranch_scc1 .Lp9x_decode
.Lp9x_restore:
	s_waitcnt vmcnt(0)
	s_barrier
	v_cmp_eq_u32_e32 vcc, 0, v146
	s_and_saveexec_b64 s[4:5], vcc
	s_cbranch_execz .Lp9x_pub
	v_mov_b32_e32 v1, 0x6600
	v_mov_b32_e32 v2, 1
	global_atomic_add v1, v2, s[94:95]
.Lp9x_pub:
	s_or_b64 exec, exec, s[4:5]
	s_mov_b32 s2, s98
	s_mov_b32 s3, s99
	s_mov_b32 s23, s100

.LBB0_888:
	v_cmp_eq_u32_e32 vcc, 0, v146
	s_and_saveexec_b64 s[98:99], vcc
	s_cbranch_execz .Lw2_done
	v_mov_b32_e32 v1, 0x6600
	s_mov_b32 s100, 0
.Lw2_poll:
	global_load_dword v2, v1, s[94:95] sc1
	s_waitcnt vmcnt(0)
	v_cmp_gt_u32_e32 vcc, 0x80, v2
	s_cbranch_vccz .Lw2_done
	s_sleep 2
	s_add_i32 s100, s100, 1
	s_cmp_lt_u32 s100, 0x20000
	s_cbranch_scc1 .Lw2_poll
.Lw2_done:
	s_or_b64 exec, exec, s[98:99]
	s_barrier
	s_cmp_lt_i32 s90, 11
	s_cselect_b64 s[2:3], -1, 0
	s_and_b64 s[2:3], s[2:3], s[0:1]
	s_andn2_b64 vcc, exec, s[2:3]
	s_cbranch_vccnz .LBB0_917
	s_cmpk_gt_i32 s72, 0xff
	v_readfirstlane_b32 s4, v146
	s_cbranch_scc1 .LBB0_917
	s_ashr_i32 s28, s72, 31
	s_lshr_b32 s0, s28, 29
	s_add_i32 s6, s72, s0
	s_and_b32 s0, s6, -8
	s_sub_i32 s7, s72, s0
	s_cmp_gt_i32 s7, -1
	s_cbranch_scc0 .LBB0_892
	s_lshl_b32 s5, s7, 5
	s_ashr_i32 s6, s6, 3
	s_cbranch_execz .LBB0_893
	s_branch .LBB0_894
